# attention units: one static priority raise for the second wave of each SIMD (waves 4-7), reset at unit end
# speedup vs baseline: 1.0053x; 1.0010x over previous
.LBB0_775:
	s_or_b64 exec, exec, s[4:5]
	s_and_b32 s60, s40, 0xff
	s_lshr_b32 s61, s60, 3
	s_sub_u32 s61, 15, s61
	s_and_b32 s64, s60, 7
	s_lshl_b32 s65, s44, 1
	s_lshl_b32 s45, s61, 2
	s_add_u32 s45, s45, 4
	s_sub_u32 s72, s45, 4
	v_lshrrev_b32_e32 v0, 6, v236
	s_nop 0
	v_readfirstlane_b32 s47, v0
	s_lshl_b32 s66, s64, 22
	s_lshr_b32 s67, s65, 1
	s_lshl_b32 s67, s67, 7
	s_add_u32 s48, s82, 0x9000000
	s_addc_u32 s49, s83, 0
	s_add_u32 s48, s48, s66
	s_addc_u32 s49, s49, 0
	s_add_u32 s48, s48, s67
	s_addc_u32 s49, s49, 0
	s_lshr_b32 s63, s65, 2
	s_lshl_b32 s63, s63, 8
	s_add_u32 s50, s82, 0xb000000
	s_addc_u32 s51, s83, 0
	s_add_u32 s50, s50, s66
	s_addc_u32 s51, s51, 0
	s_add_u32 s50, s50, s63
	s_addc_u32 s51, s51, 0
	s_lshl_b32 s63, s61, 8
	s_lshl_b32 s60, s47, 5
	s_add_u32 s63, s63, s60
	s_lshl_b32 s60, s63, 10
	s_add_u32 s54, s82, 0x7000000
	s_addc_u32 s55, s83, 0
	s_add_u32 s54, s54, s66
	s_addc_u32 s55, s55, 0
	s_add_u32 s54, s54, s60
	s_addc_u32 s55, s55, 0
	s_add_u32 s54, s54, s67
	s_addc_u32 s55, s55, 0
	s_lshl_b32 s60, s64, 12
	s_add_u32 s60, s60, s63
	s_lshl_b32 s60, s60, 11
	s_and_b32 s67, s65, 14
	s_lshl_b32 s67, s67, 7
	s_add_u32 s52, s82, 0x16000000
	s_addc_u32 s53, s83, 0
	s_add_u32 s52, s52, s60
	s_addc_u32 s53, s53, 0
	s_add_u32 s52, s52, s67
	s_addc_u32 s53, s53, 0
	v_and_b32_e32 v237, 63, v236
	v_lshrrev_b32_e32 v252, 5, v237
	v_and_b32_e32 v0, 31, v237
	s_lshl_b32 s60, s47, 4
	v_lshl_add_u32 v238, v237, 10, s60
	s_and_b32 s60, s47, 3
	s_lshl_b32 s60, s60, 14
	s_lshr_b32 s61, s47, 2
	s_lshl_b32 s61, s61, 6
	s_add_u32 s60, s60, s61
	v_lshrrev_b32_e32 v1, 2, v237
	v_lshlrev_b32_e32 v1, 10, v1
	v_and_b32_e32 v2, 3, v237
	v_lshl_or_b32 v1, v2, 4, v1
	v_add_u32_e32 v239, s60, v1
	v_lshlrev_b32_e32 v244, 10, v252
	v_lshl_or_b32 v244, v0, 4, v244
	v_bfe_u32 v1, v237, 4, 1
	v_lshlrev_b32_e32 v1, 5, v1
	v_lshl_or_b32 v1, v2, 3, v1
	v_bfe_u32 v2, v237, 2, 2
	v_lshl_or_b32 v2, v252, 2, v2
	v_lshl_or_b32 v1, v2, 6, v1
	v_add_u32_e32 v245, 24576, v1
	s_lshl_b32 s60, s47, 5
	v_add_u32_e32 v246, s60, v0
	s_cmp_ge_u32 s47, 4
	s_cbranch_scc0 .Lat_noprio
	s_setprio 1
.Lat_noprio:
	s_lshl_b32 s60, s47, 8
	s_add_u32 s60, s60, 73728
	v_mov_b32_e32 v249, s60
	s_lshl_b32 s70, s47, 10
	s_add_u32 s71, s70, 24576
	s_mov_b64 s[74:75], s[48:49]
	s_mov_b64 s[76:77], s[50:51]
	s_mov_b32 s56, 0x4000
	s_mov_b32 s57, 0
	s_mov_b32 s58, 0x2000
	s_add_i32 m0, s57, s70
	s_nop 0
	global_load_lds_dwordx4 v238, s[74:75]
	s_add_u32 s74, s74, 0x10000
	s_addc_u32 s75, s75, 0
	s_lshl_b32 s60, s57, 1
	s_add_i32 s60, s60, s71
	s_mov_b32 m0, s60
	s_nop 0
	global_load_lds_dwordx4 v239, s[76:77]
	s_add_u32 s62, s76, 0x80
	s_addc_u32 s63, s77, 0
	s_add_i32 m0, s60, 0x2000
	s_nop 0
	global_load_lds_dwordx4 v239, s[62:63]
	s_add_u32 s76, s76, 0x10000
	s_addc_u32 s77, s77, 0
	s_add_i32 m0, s58, s70
	s_nop 0
	global_load_lds_dwordx4 v238, s[74:75]
	s_add_u32 s74, s74, 0x10000
	s_addc_u32 s75, s75, 0
	v_lshlrev_b32_e32 v1, 10, v0
	v_lshl_or_b32 v1, v252, 4, v1
	global_load_dwordx4 v[16:19], v1, s[54:55]
	global_load_dwordx4 v[20:23], v1, s[54:55] offset:32
	global_load_dwordx4 v[24:27], v1, s[54:55] offset:64
	global_load_dwordx4 v[28:31], v1, s[54:55] offset:96
	s_add_i32 m0, s56, s70
	s_nop 0
	global_load_lds_dwordx4 v238, s[74:75]
	s_add_u32 s74, s74, 0x10000
	s_addc_u32 s75, s75, 0
	v_mov_b32_e32 v248, 0
	v_mov_b32_e32 v247, 0
	v_mov_b32_e32 v160, 0
	v_mov_b32_e32 v161, 0
	v_mov_b32_e32 v162, 0
	v_mov_b32_e32 v163, 0
	v_mov_b32_e32 v164, 0
	v_mov_b32_e32 v165, 0
	v_mov_b32_e32 v166, 0
	v_mov_b32_e32 v167, 0
	v_mov_b32_e32 v168, 0
	v_mov_b32_e32 v169, 0
	v_mov_b32_e32 v170, 0
	v_mov_b32_e32 v171, 0
	v_mov_b32_e32 v172, 0
	v_mov_b32_e32 v173, 0
	v_mov_b32_e32 v174, 0
	v_mov_b32_e32 v175, 0
	v_mov_b32_e32 v32, 0
	v_mov_b32_e32 v33, 0
	v_mov_b32_e32 v34, 0
	v_mov_b32_e32 v35, 0
	v_mov_b32_e32 v36, 0
	v_mov_b32_e32 v37, 0
	v_mov_b32_e32 v38, 0
	v_mov_b32_e32 v39, 0
	v_mov_b32_e32 v40, 0
	v_mov_b32_e32 v41, 0
	v_mov_b32_e32 v42, 0
	v_mov_b32_e32 v43, 0
	v_mov_b32_e32 v44, 0
	v_mov_b32_e32 v45, 0
	v_mov_b32_e32 v46, 0
	v_mov_b32_e32 v47, 0
	v_mov_b32_e32 v48, 0
	v_mov_b32_e32 v49, 0
	v_mov_b32_e32 v50, 0
	v_mov_b32_e32 v51, 0
	v_mov_b32_e32 v52, 0
	v_mov_b32_e32 v53, 0
	v_mov_b32_e32 v54, 0
	v_mov_b32_e32 v55, 0
	v_mov_b32_e32 v56, 0
	v_mov_b32_e32 v57, 0
	v_mov_b32_e32 v58, 0
	v_mov_b32_e32 v59, 0
	v_mov_b32_e32 v60, 0
	v_mov_b32_e32 v61, 0
	v_mov_b32_e32 v62, 0
	v_mov_b32_e32 v63, 0
	v_mov_b32_e32 v64, 0
	v_mov_b32_e32 v65, 0
	v_mov_b32_e32 v66, 0
	v_mov_b32_e32 v67, 0
	v_mov_b32_e32 v68, 0
	v_mov_b32_e32 v69, 0
	v_mov_b32_e32 v70, 0
	v_mov_b32_e32 v71, 0
	v_mov_b32_e32 v72, 0
	v_mov_b32_e32 v73, 0
	v_mov_b32_e32 v74, 0
	v_mov_b32_e32 v75, 0
	v_mov_b32_e32 v76, 0
	v_mov_b32_e32 v77, 0
	v_mov_b32_e32 v78, 0
	v_mov_b32_e32 v79, 0
	v_mov_b32_e32 v80, 0
	v_mov_b32_e32 v81, 0
	v_mov_b32_e32 v82, 0
	v_mov_b32_e32 v83, 0
	v_mov_b32_e32 v84, 0
	v_mov_b32_e32 v85, 0
	v_mov_b32_e32 v86, 0
	v_mov_b32_e32 v87, 0
	v_mov_b32_e32 v88, 0
	v_mov_b32_e32 v89, 0
	v_mov_b32_e32 v90, 0
	v_mov_b32_e32 v91, 0
	v_mov_b32_e32 v92, 0
	v_mov_b32_e32 v93, 0
	v_mov_b32_e32 v94, 0
	v_mov_b32_e32 v95, 0
	s_mov_b32 s46, 0
	s_waitcnt vmcnt(8) lgkmcnt(0)
	s_barrier
	v_add_u32_e32 v250, s57, v244
	ds_read_b128 v[208:211], v250
	ds_read_b128 v[212:215], v250 offset:512
	ds_read_b128 v[216:219], v250 offset:2048
	ds_read_b128 v[220:223], v250 offset:2560
	ds_read_b128 v[224:227], v250 offset:4096
	ds_read_b128 v[228:231], v250 offset:4608
	ds_read_b128 v[232:235], v250 offset:6144
	ds_read_b128 v[240:243], v250 offset:6656
	s_waitcnt vmcnt(1) lgkmcnt(0)
	v_mfma_f32_32x32x16_bf16 v[96:111], v[208:211], v[16:19], v[160:175]
	v_mfma_f32_32x32x16_bf16 v[112:127], v[212:215], v[16:19], v[160:175]
	v_mfma_f32_32x32x16_bf16 v[96:111], v[216:219], v[20:23], v[96:111]
	v_mfma_f32_32x32x16_bf16 v[112:127], v[220:223], v[20:23], v[112:127]
	v_mfma_f32_32x32x16_bf16 v[96:111], v[224:227], v[24:27], v[96:111]
	v_mfma_f32_32x32x16_bf16 v[112:127], v[228:231], v[24:27], v[112:127]
	v_mfma_f32_32x32x16_bf16 v[96:111], v[232:235], v[28:31], v[96:111]
	v_mfma_f32_32x32x16_bf16 v[112:127], v[240:243], v[28:31], v[112:127]
	s_nop 7
	s_nop 7
	s_cmp_lt_u32 s46, s72
	s_cbranch_scc1 .Lat_nomask_230
	s_sub_u32 s60, s46, s72
	s_lshl_b32 s60, s60, 6
	v_lshl_add_u32 v0, v252, 2, s60
	v_sub_u32_e32 v0, v246, v0
	v_mov_b32_e32 v1, 0xff800000
	v_cmp_gt_i32_e64 s[60:61], 0, v0
	v_cmp_gt_i32_e64 s[62:63], 32, v0
	v_cmp_gt_i32_e64 s[64:65], 1, v0
	v_cmp_gt_i32_e64 s[66:67], 33, v0
	v_cndmask_b32_e64 v96, v96, v1, s[60:61]
	v_cmp_gt_i32_e64 s[60:61], 2, v0
	v_cndmask_b32_e64 v112, v112, v1, s[62:63]
	v_cmp_gt_i32_e64 s[62:63], 34, v0
	v_cndmask_b32_e64 v97, v97, v1, s[64:65]
	v_cmp_gt_i32_e64 s[64:65], 3, v0
	v_cndmask_b32_e64 v113, v113, v1, s[66:67]
	v_cmp_gt_i32_e64 s[66:67], 35, v0
	v_cndmask_b32_e64 v98, v98, v1, s[60:61]
	v_cmp_gt_i32_e64 s[60:61], 8, v0
	v_cndmask_b32_e64 v114, v114, v1, s[62:63]
	v_cmp_gt_i32_e64 s[62:63], 40, v0
	v_cndmask_b32_e64 v99, v99, v1, s[64:65]
	v_cmp_gt_i32_e64 s[64:65], 9, v0
	v_cndmask_b32_e64 v115, v115, v1, s[66:67]
	v_cmp_gt_i32_e64 s[66:67], 41, v0
	v_cndmask_b32_e64 v100, v100, v1, s[60:61]
	v_cmp_gt_i32_e64 s[60:61], 10, v0
	v_cndmask_b32_e64 v116, v116, v1, s[62:63]
	v_cmp_gt_i32_e64 s[62:63], 42, v0
	v_cndmask_b32_e64 v101, v101, v1, s[64:65]
	v_cmp_gt_i32_e64 s[64:65], 11, v0
	v_cndmask_b32_e64 v117, v117, v1, s[66:67]
	v_cmp_gt_i32_e64 s[66:67], 43, v0
	v_cndmask_b32_e64 v102, v102, v1, s[60:61]
	v_cmp_gt_i32_e64 s[60:61], 16, v0
	v_cndmask_b32_e64 v118, v118, v1, s[62:63]
	v_cmp_gt_i32_e64 s[62:63], 48, v0
	v_cndmask_b32_e64 v103, v103, v1, s[64:65]
	v_cmp_gt_i32_e64 s[64:65], 17, v0
	v_cndmask_b32_e64 v119, v119, v1, s[66:67]
	v_cmp_gt_i32_e64 s[66:67], 49, v0
	v_cndmask_b32_e64 v104, v104, v1, s[60:61]
	v_cmp_gt_i32_e64 s[60:61], 18, v0
	v_cndmask_b32_e64 v120, v120, v1, s[62:63]
	v_cmp_gt_i32_e64 s[62:63], 50, v0
	v_cndmask_b32_e64 v105, v105, v1, s[64:65]
	v_cmp_gt_i32_e64 s[64:65], 19, v0
	v_cndmask_b32_e64 v121, v121, v1, s[66:67]
	v_cmp_gt_i32_e64 s[66:67], 51, v0
	v_cndmask_b32_e64 v106, v106, v1, s[60:61]
	v_cmp_gt_i32_e64 s[60:61], 24, v0
	v_cndmask_b32_e64 v122, v122, v1, s[62:63]
	v_cmp_gt_i32_e64 s[62:63], 56, v0
	v_cndmask_b32_e64 v107, v107, v1, s[64:65]
	v_cmp_gt_i32_e64 s[64:65], 25, v0
	v_cndmask_b32_e64 v123, v123, v1, s[66:67]
	v_cmp_gt_i32_e64 s[66:67], 57, v0
	v_cndmask_b32_e64 v108, v108, v1, s[60:61]
	v_cmp_gt_i32_e64 s[60:61], 26, v0
	v_cndmask_b32_e64 v124, v124, v1, s[62:63]
	v_cmp_gt_i32_e64 s[62:63], 58, v0
	v_cndmask_b32_e64 v109, v109, v1, s[64:65]
	v_cmp_gt_i32_e64 s[64:65], 27, v0
	v_cndmask_b32_e64 v125, v125, v1, s[66:67]
	v_cmp_gt_i32_e64 s[66:67], 59, v0
	v_cndmask_b32_e64 v110, v110, v1, s[60:61]
	s_nop 1
	v_cndmask_b32_e64 v126, v126, v1, s[62:63]
	v_cndmask_b32_e64 v111, v111, v1, s[64:65]
	v_cndmask_b32_e64 v127, v127, v1, s[66:67]

.Lat_drain:
	v_add_f32_e32 v247, v247, v128
	v_add_f32_e32 v247, v247, v129
	v_add_f32_e32 v247, v247, v130
	v_add_f32_e32 v247, v247, v131
	v_cvt_pk_bf16_f32 v176, v128, v129
	v_cvt_pk_bf16_f32 v177, v130, v131
	v_add_f32_e32 v247, v247, v132
	v_add_f32_e32 v247, v247, v133
	v_add_f32_e32 v247, v247, v134
	v_add_f32_e32 v247, v247, v135
	v_cvt_pk_bf16_f32 v178, v132, v133
	v_cvt_pk_bf16_f32 v179, v134, v135
	v_add_f32_e32 v247, v247, v136
	v_add_f32_e32 v247, v247, v137
	v_add_f32_e32 v247, v247, v138
	v_add_f32_e32 v247, v247, v139
	v_cvt_pk_bf16_f32 v180, v136, v137
	v_cvt_pk_bf16_f32 v181, v138, v139
	v_add_f32_e32 v247, v247, v140
	v_add_f32_e32 v247, v247, v141
	v_add_f32_e32 v247, v247, v142
	v_add_f32_e32 v247, v247, v143
	v_cvt_pk_bf16_f32 v182, v140, v141
	v_cvt_pk_bf16_f32 v183, v142, v143
	v_add_f32_e32 v247, v247, v144
	v_add_f32_e32 v247, v247, v145
	v_add_f32_e32 v247, v247, v146
	v_add_f32_e32 v247, v247, v147
	v_cvt_pk_bf16_f32 v184, v144, v145
	v_cvt_pk_bf16_f32 v185, v146, v147
	v_add_f32_e32 v247, v247, v148
	v_add_f32_e32 v247, v247, v149
	v_add_f32_e32 v247, v247, v150
	v_add_f32_e32 v247, v247, v151
	v_cvt_pk_bf16_f32 v186, v148, v149
	v_cvt_pk_bf16_f32 v187, v150, v151
	v_add_f32_e32 v247, v247, v152
	v_add_f32_e32 v247, v247, v153
	v_add_f32_e32 v247, v247, v154
	v_add_f32_e32 v247, v247, v155
	v_cvt_pk_bf16_f32 v188, v152, v153
	v_cvt_pk_bf16_f32 v189, v154, v155
	v_add_f32_e32 v247, v247, v156
	v_add_f32_e32 v247, v247, v157
	v_add_f32_e32 v247, v247, v158
	v_add_f32_e32 v247, v247, v159
	v_cvt_pk_bf16_f32 v190, v156, v157
	v_cvt_pk_bf16_f32 v191, v158, v159
	s_lshl_b32 s60, s56, 1
	v_add_u32_e32 v250, s60, v245
	ds_read_b64_tr_b16 v[192:193], v250 offset:0
	ds_read_b64_tr_b16 v[194:195], v250 offset:512
	ds_read_b64_tr_b16 v[196:197], v250 offset:4096
	ds_read_b64_tr_b16 v[198:199], v250 offset:4608
	ds_read_b64_tr_b16 v[200:201], v250 offset:8192
	ds_read_b64_tr_b16 v[202:203], v250 offset:8704
	ds_read_b64_tr_b16 v[204:205], v250 offset:12288
	ds_read_b64_tr_b16 v[206:207], v250 offset:12800
	s_waitcnt lgkmcnt(6)
	v_mfma_f32_32x32x16_bf16 v[32:47], v[176:179], v[192:195], v[32:47]
	ds_read_b64_tr_b16 v[192:193], v250 offset:1024
	ds_read_b64_tr_b16 v[194:195], v250 offset:1536
	s_waitcnt lgkmcnt(6)
	v_mfma_f32_32x32x16_bf16 v[48:63], v[176:179], v[196:199], v[48:63]
	ds_read_b64_tr_b16 v[196:197], v250 offset:5120
	ds_read_b64_tr_b16 v[198:199], v250 offset:5632
	s_waitcnt lgkmcnt(6)
	v_mfma_f32_32x32x16_bf16 v[64:79], v[176:179], v[200:203], v[64:79]
	ds_read_b64_tr_b16 v[200:201], v250 offset:9216
	ds_read_b64_tr_b16 v[202:203], v250 offset:9728
	s_waitcnt lgkmcnt(6)
	v_mfma_f32_32x32x16_bf16 v[80:95], v[176:179], v[204:207], v[80:95]
	ds_read_b64_tr_b16 v[204:205], v250 offset:13312
	ds_read_b64_tr_b16 v[206:207], v250 offset:13824
	s_waitcnt lgkmcnt(6)
	v_mfma_f32_32x32x16_bf16 v[32:47], v[180:183], v[192:195], v[32:47]
	ds_read_b64_tr_b16 v[192:193], v250 offset:2048
	ds_read_b64_tr_b16 v[194:195], v250 offset:2560
	s_waitcnt lgkmcnt(6)
	v_mfma_f32_32x32x16_bf16 v[48:63], v[180:183], v[196:199], v[48:63]
	ds_read_b64_tr_b16 v[196:197], v250 offset:6144
	ds_read_b64_tr_b16 v[198:199], v250 offset:6656
	s_waitcnt lgkmcnt(6)
	v_mfma_f32_32x32x16_bf16 v[64:79], v[180:183], v[200:203], v[64:79]
	ds_read_b64_tr_b16 v[200:201], v250 offset:10240
	ds_read_b64_tr_b16 v[202:203], v250 offset:10752
	s_waitcnt lgkmcnt(6)
	v_mfma_f32_32x32x16_bf16 v[80:95], v[180:183], v[204:207], v[80:95]
	ds_read_b64_tr_b16 v[204:205], v250 offset:14336
	ds_read_b64_tr_b16 v[206:207], v250 offset:14848
	s_waitcnt lgkmcnt(6)
	v_mfma_f32_32x32x16_bf16 v[32:47], v[184:187], v[192:195], v[32:47]
	ds_read_b64_tr_b16 v[192:193], v250 offset:3072
	ds_read_b64_tr_b16 v[194:195], v250 offset:3584
	s_waitcnt lgkmcnt(6)
	v_mfma_f32_32x32x16_bf16 v[48:63], v[184:187], v[196:199], v[48:63]
	ds_read_b64_tr_b16 v[196:197], v250 offset:7168
	ds_read_b64_tr_b16 v[198:199], v250 offset:7680
	s_waitcnt lgkmcnt(6)
	v_mfma_f32_32x32x16_bf16 v[64:79], v[184:187], v[200:203], v[64:79]
	ds_read_b64_tr_b16 v[200:201], v250 offset:11264
	ds_read_b64_tr_b16 v[202:203], v250 offset:11776
	s_waitcnt lgkmcnt(6)
	v_mfma_f32_32x32x16_bf16 v[80:95], v[184:187], v[204:207], v[80:95]
	ds_read_b64_tr_b16 v[204:205], v250 offset:15360
	ds_read_b64_tr_b16 v[206:207], v250 offset:15872
	s_waitcnt lgkmcnt(6)
	v_mfma_f32_32x32x16_bf16 v[32:47], v[188:191], v[192:195], v[32:47]
	s_waitcnt lgkmcnt(4)
	v_mfma_f32_32x32x16_bf16 v[48:63], v[188:191], v[196:199], v[48:63]
	s_waitcnt lgkmcnt(2)
	v_mfma_f32_32x32x16_bf16 v[64:79], v[188:191], v[200:203], v[64:79]
	s_waitcnt lgkmcnt(0)
	v_mfma_f32_32x32x16_bf16 v[80:95], v[188:191], v[204:207], v[80:95]
	v_mov_b32_e32 v250, v247
	v_mov_b32_e32 v251, v247
	s_nop 1
	v_permlane32_swap_b32_e32 v250, v251
	v_add_f32_e32 v250, v250, v251
	s_waitcnt vmcnt(0) lgkmcnt(0)
	s_barrier
	v_and_b32_e32 v244, 31, v237
	v_lshl_add_u32 v244, v244, 2, v249
	v_cmp_eq_u32_e32 vcc, 0, v252
	s_and_saveexec_b64 s[60:61], vcc
	ds_write_b32 v244, v250 offset:128
	s_or_b64 exec, exec, s[60:61]
	s_waitcnt lgkmcnt(0)
	v_lshl_add_u32 v250, v252, 4, v249
	ds_read_b128 v[0:3], v250 offset:128
	ds_read_b128 v[4:7], v250 offset:160
	ds_read_b128 v[8:11], v250 offset:192
	ds_read_b128 v[12:15], v250 offset:224
	s_waitcnt lgkmcnt(0)
	v_rcp_f32_e32 v0, v0
	v_rcp_f32_e32 v1, v1
	v_rcp_f32_e32 v2, v2
	v_rcp_f32_e32 v3, v3
	v_rcp_f32_e32 v4, v4
	v_rcp_f32_e32 v5, v5
	v_rcp_f32_e32 v6, v6
	v_rcp_f32_e32 v7, v7
	v_rcp_f32_e32 v8, v8
	v_rcp_f32_e32 v9, v9
	v_rcp_f32_e32 v10, v10
	v_rcp_f32_e32 v11, v11
	v_rcp_f32_e32 v12, v12
	v_rcp_f32_e32 v13, v13
	v_rcp_f32_e32 v14, v14
	v_rcp_f32_e32 v15, v15
	s_nop 7
	s_nop 7
	s_lshl_b32 s60, s47, 13
	v_and_b32_e32 v250, 31, v237
	v_lshlrev_b32_e32 v250, 1, v250
	v_add_u32_e32 v250, s60, v250
	v_lshlrev_b32_e32 v251, 10, v252
	v_add_u32_e32 v250, v250, v251
	v_mul_f32_e32 v251, v32, v0
	v_cvt_pk_bf16_f32 v251, v251, v251
	ds_write_b16 v250, v251 offset:0
	v_mul_f32_e32 v251, v48, v0
	v_cvt_pk_bf16_f32 v251, v251, v251
	ds_write_b16 v250, v251 offset:64
	v_mul_f32_e32 v251, v64, v0
	v_cvt_pk_bf16_f32 v251, v251, v251
	ds_write_b16 v250, v251 offset:128
	v_mul_f32_e32 v251, v80, v0
	v_cvt_pk_bf16_f32 v251, v251, v251
	ds_write_b16 v250, v251 offset:192
	v_mul_f32_e32 v251, v33, v1
	v_cvt_pk_bf16_f32 v251, v251, v251
	ds_write_b16 v250, v251 offset:256
	v_mul_f32_e32 v251, v49, v1
	v_cvt_pk_bf16_f32 v251, v251, v251
	ds_write_b16 v250, v251 offset:320
	v_mul_f32_e32 v251, v65, v1
	v_cvt_pk_bf16_f32 v251, v251, v251
	ds_write_b16 v250, v251 offset:384
	v_mul_f32_e32 v251, v81, v1
	v_cvt_pk_bf16_f32 v251, v251, v251
	ds_write_b16 v250, v251 offset:448
	v_mul_f32_e32 v251, v34, v2
	v_cvt_pk_bf16_f32 v251, v251, v251
	ds_write_b16 v250, v251 offset:512
	v_mul_f32_e32 v251, v50, v2
	v_cvt_pk_bf16_f32 v251, v251, v251
	ds_write_b16 v250, v251 offset:576
	v_mul_f32_e32 v251, v66, v2
	v_cvt_pk_bf16_f32 v251, v251, v251
	ds_write_b16 v250, v251 offset:640
	v_mul_f32_e32 v251, v82, v2
	v_cvt_pk_bf16_f32 v251, v251, v251
	ds_write_b16 v250, v251 offset:704
	v_mul_f32_e32 v251, v35, v3
	v_cvt_pk_bf16_f32 v251, v251, v251
	ds_write_b16 v250, v251 offset:768
	v_mul_f32_e32 v251, v51, v3
	v_cvt_pk_bf16_f32 v251, v251, v251
	ds_write_b16 v250, v251 offset:832
	v_mul_f32_e32 v251, v67, v3
	v_cvt_pk_bf16_f32 v251, v251, v251
	ds_write_b16 v250, v251 offset:896
	v_mul_f32_e32 v251, v83, v3
	v_cvt_pk_bf16_f32 v251, v251, v251
	ds_write_b16 v250, v251 offset:960
	v_mul_f32_e32 v251, v36, v4
	v_cvt_pk_bf16_f32 v251, v251, v251
	ds_write_b16 v250, v251 offset:2048
	v_mul_f32_e32 v251, v52, v4
	v_cvt_pk_bf16_f32 v251, v251, v251
	ds_write_b16 v250, v251 offset:2112
	v_mul_f32_e32 v251, v68, v4
	v_cvt_pk_bf16_f32 v251, v251, v251
	ds_write_b16 v250, v251 offset:2176
	v_mul_f32_e32 v251, v84, v4
	v_cvt_pk_bf16_f32 v251, v251, v251
	ds_write_b16 v250, v251 offset:2240
	v_mul_f32_e32 v251, v37, v5
	v_cvt_pk_bf16_f32 v251, v251, v251
	ds_write_b16 v250, v251 offset:2304
	v_mul_f32_e32 v251, v53, v5
	v_cvt_pk_bf16_f32 v251, v251, v251
	ds_write_b16 v250, v251 offset:2368
	v_mul_f32_e32 v251, v69, v5
	v_cvt_pk_bf16_f32 v251, v251, v251
	ds_write_b16 v250, v251 offset:2432
	v_mul_f32_e32 v251, v85, v5
	v_cvt_pk_bf16_f32 v251, v251, v251
	ds_write_b16 v250, v251 offset:2496
	v_mul_f32_e32 v251, v38, v6
	v_cvt_pk_bf16_f32 v251, v251, v251
	ds_write_b16 v250, v251 offset:2560
	v_mul_f32_e32 v251, v54, v6
	v_cvt_pk_bf16_f32 v251, v251, v251
	ds_write_b16 v250, v251 offset:2624
	v_mul_f32_e32 v251, v70, v6
	v_cvt_pk_bf16_f32 v251, v251, v251
	ds_write_b16 v250, v251 offset:2688
	v_mul_f32_e32 v251, v86, v6
	v_cvt_pk_bf16_f32 v251, v251, v251
	ds_write_b16 v250, v251 offset:2752
	v_mul_f32_e32 v251, v39, v7
	v_cvt_pk_bf16_f32 v251, v251, v251
	ds_write_b16 v250, v251 offset:2816
	v_mul_f32_e32 v251, v55, v7
	v_cvt_pk_bf16_f32 v251, v251, v251
	ds_write_b16 v250, v251 offset:2880
	v_mul_f32_e32 v251, v71, v7
	v_cvt_pk_bf16_f32 v251, v251, v251
	ds_write_b16 v250, v251 offset:2944
	v_mul_f32_e32 v251, v87, v7
	v_cvt_pk_bf16_f32 v251, v251, v251
	ds_write_b16 v250, v251 offset:3008
	v_mul_f32_e32 v251, v40, v8
	v_cvt_pk_bf16_f32 v251, v251, v251
	ds_write_b16 v250, v251 offset:4096
	v_mul_f32_e32 v251, v56, v8
	v_cvt_pk_bf16_f32 v251, v251, v251
	ds_write_b16 v250, v251 offset:4160
	v_mul_f32_e32 v251, v72, v8
	v_cvt_pk_bf16_f32 v251, v251, v251
	ds_write_b16 v250, v251 offset:4224
	v_mul_f32_e32 v251, v88, v8
	v_cvt_pk_bf16_f32 v251, v251, v251
	ds_write_b16 v250, v251 offset:4288
	v_mul_f32_e32 v251, v41, v9
	v_cvt_pk_bf16_f32 v251, v251, v251
	ds_write_b16 v250, v251 offset:4352
	v_mul_f32_e32 v251, v57, v9
	v_cvt_pk_bf16_f32 v251, v251, v251
	ds_write_b16 v250, v251 offset:4416
	v_mul_f32_e32 v251, v73, v9
	v_cvt_pk_bf16_f32 v251, v251, v251
	ds_write_b16 v250, v251 offset:4480
	v_mul_f32_e32 v251, v89, v9
	v_cvt_pk_bf16_f32 v251, v251, v251
	ds_write_b16 v250, v251 offset:4544
	v_mul_f32_e32 v251, v42, v10
	v_cvt_pk_bf16_f32 v251, v251, v251
	ds_write_b16 v250, v251 offset:4608
	v_mul_f32_e32 v251, v58, v10
	v_cvt_pk_bf16_f32 v251, v251, v251
	ds_write_b16 v250, v251 offset:4672
	v_mul_f32_e32 v251, v74, v10
	v_cvt_pk_bf16_f32 v251, v251, v251
	ds_write_b16 v250, v251 offset:4736
	v_mul_f32_e32 v251, v90, v10
	v_cvt_pk_bf16_f32 v251, v251, v251
	ds_write_b16 v250, v251 offset:4800
	v_mul_f32_e32 v251, v43, v11
	v_cvt_pk_bf16_f32 v251, v251, v251
	ds_write_b16 v250, v251 offset:4864
	v_mul_f32_e32 v251, v59, v11
	v_cvt_pk_bf16_f32 v251, v251, v251
	ds_write_b16 v250, v251 offset:4928
	v_mul_f32_e32 v251, v75, v11
	v_cvt_pk_bf16_f32 v251, v251, v251
	ds_write_b16 v250, v251 offset:4992
	v_mul_f32_e32 v251, v91, v11
	v_cvt_pk_bf16_f32 v251, v251, v251
	ds_write_b16 v250, v251 offset:5056
	v_mul_f32_e32 v251, v44, v12
	v_cvt_pk_bf16_f32 v251, v251, v251
	ds_write_b16 v250, v251 offset:6144
	v_mul_f32_e32 v251, v60, v12
	v_cvt_pk_bf16_f32 v251, v251, v251
	ds_write_b16 v250, v251 offset:6208
	v_mul_f32_e32 v251, v76, v12
	v_cvt_pk_bf16_f32 v251, v251, v251
	ds_write_b16 v250, v251 offset:6272
	v_mul_f32_e32 v251, v92, v12
	v_cvt_pk_bf16_f32 v251, v251, v251
	ds_write_b16 v250, v251 offset:6336
	v_mul_f32_e32 v251, v45, v13
	v_cvt_pk_bf16_f32 v251, v251, v251
	ds_write_b16 v250, v251 offset:6400
	v_mul_f32_e32 v251, v61, v13
	v_cvt_pk_bf16_f32 v251, v251, v251
	ds_write_b16 v250, v251 offset:6464
	v_mul_f32_e32 v251, v77, v13
	v_cvt_pk_bf16_f32 v251, v251, v251
	ds_write_b16 v250, v251 offset:6528
	v_mul_f32_e32 v251, v93, v13
	v_cvt_pk_bf16_f32 v251, v251, v251
	ds_write_b16 v250, v251 offset:6592
	v_mul_f32_e32 v251, v46, v14
	v_cvt_pk_bf16_f32 v251, v251, v251
	ds_write_b16 v250, v251 offset:6656
	v_mul_f32_e32 v251, v62, v14
	v_cvt_pk_bf16_f32 v251, v251, v251
	ds_write_b16 v250, v251 offset:6720
	v_mul_f32_e32 v251, v78, v14
	v_cvt_pk_bf16_f32 v251, v251, v251
	ds_write_b16 v250, v251 offset:6784
	v_mul_f32_e32 v251, v94, v14
	v_cvt_pk_bf16_f32 v251, v251, v251
	ds_write_b16 v250, v251 offset:6848
	v_mul_f32_e32 v251, v47, v15
	v_cvt_pk_bf16_f32 v251, v251, v251
	ds_write_b16 v250, v251 offset:6912
	v_mul_f32_e32 v251, v63, v15
	v_cvt_pk_bf16_f32 v251, v251, v251
	ds_write_b16 v250, v251 offset:6976
	v_mul_f32_e32 v251, v79, v15
	v_cvt_pk_bf16_f32 v251, v251, v251
	ds_write_b16 v250, v251 offset:7040
	v_mul_f32_e32 v251, v95, v15
	v_cvt_pk_bf16_f32 v251, v251, v251
	ds_write_b16 v250, v251 offset:7104
	s_waitcnt lgkmcnt(0)
	v_lshrrev_b32_e32 v251, 4, v237
	v_and_b32_e32 v244, 15, v237
	v_lshlrev_b32_e32 v245, 8, v251
	v_lshl_or_b32 v245, v244, 4, v245
	v_add_u32_e32 v245, s60, v245
	v_lshlrev_b32_e32 v246, 11, v251
	v_lshl_or_b32 v246, v244, 4, v246
	ds_read_b128 v[16:19], v245 offset:0
	s_waitcnt lgkmcnt(0)
	global_store_dwordx4 v246, v[16:19], s[52:53]
	v_add_u32_e32 v246, 0x2000, v246
	s_nop 1
	ds_read_b128 v[16:19], v245 offset:1024
	s_waitcnt lgkmcnt(0)
	global_store_dwordx4 v246, v[16:19], s[52:53]
	v_add_u32_e32 v246, 0x2000, v246
	s_nop 1
	ds_read_b128 v[16:19], v245 offset:2048
	s_waitcnt lgkmcnt(0)
	global_store_dwordx4 v246, v[16:19], s[52:53]
	v_add_u32_e32 v246, 0x2000, v246
	s_nop 1
	ds_read_b128 v[16:19], v245 offset:3072
	s_waitcnt lgkmcnt(0)
	global_store_dwordx4 v246, v[16:19], s[52:53]
	v_add_u32_e32 v246, 0x2000, v246
	s_nop 1
	ds_read_b128 v[16:19], v245 offset:4096
	s_waitcnt lgkmcnt(0)
	global_store_dwordx4 v246, v[16:19], s[52:53]
	v_add_u32_e32 v246, 0x2000, v246
	s_nop 1
	ds_read_b128 v[16:19], v245 offset:5120
	s_waitcnt lgkmcnt(0)
	global_store_dwordx4 v246, v[16:19], s[52:53]
	v_add_u32_e32 v246, 0x2000, v246
	s_nop 1
	ds_read_b128 v[16:19], v245 offset:6144
	s_waitcnt lgkmcnt(0)
	global_store_dwordx4 v246, v[16:19], s[52:53]
	v_add_u32_e32 v246, 0x2000, v246
	s_nop 1
	ds_read_b128 v[16:19], v245 offset:7168
	s_waitcnt lgkmcnt(0)
	global_store_dwordx4 v246, v[16:19], s[52:53]
	v_add_u32_e32 v246, 0x2000, v246
	s_nop 1
	s_setprio 0
	s_waitcnt lgkmcnt(0)
	s_barrier
